# dnprep: raw-tile prefetch issued after the conv-weight wait, explicit wait before the next RAWPUT
# speedup vs baseline: 1.0019x; 1.0019x over previous
; __device__ __forceinline__ void phase_dnprep(KP kp_){ asm volatile("" : "+s"(kp_)); const Params p=load_params(kp_);
;     ...
;       RAWPUT1(rp0,tid); RAWPUT1(rp1,tid+512); RAWPUT1(rp2,tid+1024);
.LBB0_666:
	s_nop 0
	s_waitcnt vmcnt(0)
	v_lshlrev_b32_e32 v2, 5, v46
	v_cmp_gt_i32_e32 vcc, s64, v46
	v_and_b32_e32 v0, 0x1e0, v2
	s_and_saveexec_b64 s[10:11], vcc
	s_cbranch_execz .LBB0_668
	v_and_b32_e32 v2, 0xfffffe00, v2
	v_add3_u32 v2, 0, v2, v0
	v_lshlrev_b32_e32 v16, 16, v4
	v_and_b32_e32 v17, 0xffff0000, v4
	v_lshlrev_b32_e32 v18, 16, v5
	v_and_b32_e32 v19, 0xffff0000, v5
	ds_write_b128 v2, v[16:19]
	v_lshlrev_b32_e32 v16, 16, v6
	v_and_b32_e32 v17, 0xffff0000, v6
	v_lshlrev_b32_e32 v18, 16, v7
	v_and_b32_e32 v19, 0xffff0000, v7
	ds_write_b128 v2, v[16:19] offset:16

; #define RAWLOAD(w_) RAWLOAD_AT(w_,tok0,rs,re,h)
; __device__ __forceinline__ void phase_dnprep(KP kp_){ asm volatile("" : "+s"(kp_)); const Params p=load_params(kp_);
;     ...
;       if (which<2) RAWLOAD(which+1);
;       __syncthreads();
;       int c=tid&127, tg=tid>>7; int ch=which*1024+h*128+c;
;       float w0=p.dn_conv_w[ch], w1=p.dn_conv_w[3072+ch], w2=p.dn_conv_w[6144+ch], w3=p.dn_conv_w[9216+ch], w4=p.dn_conv_w[12288+ch];
;       float o16[16];
;       { float rw[20];
;         _Pragma("unroll") for (int i=0;i<20;++i) rw[i]=raw[(tg*16+i)*128+c];
.LBB0_672:
	s_or_b64 exec, exec, s[12:13]
	s_cmpk_lg_i32 s40, 0x1000
	s_cselect_b64 s[42:43], -1, 0
	s_cmpk_eq_i32 s40, 0x1000
	s_movk_i32 s12, 0x800
	s_cbranch_scc1 .LBB0_680
	s_mov_b32 s12, s74
.LBB0_680:
	v_and_b32_e32 v50, 0x7f, v46
	s_or_b32 s12, s18, s12
	v_or_b32_e32 v0, s12, v50
	v_lshl_add_u64 v[2:3], v[0:1], 2, s[20:21]
	v_add_co_u32_e32 v16, vcc, 0x3000, v2
	s_waitcnt lgkmcnt(0)
	s_nop 0
	v_addc_co_u32_e32 v17, vcc, 0, v3, vcc
	v_add_co_u32_e32 v18, vcc, s63, v2
	s_barrier
	s_nop 0
	v_addc_co_u32_e32 v19, vcc, 0, v3, vcc
	v_add_co_u32_e32 v20, vcc, 0x9000, v2
	s_nop 1
	v_addc_co_u32_e32 v21, vcc, 0, v3, vcc
	flat_load_dword v0, v[2:3]
	flat_load_dword v28, v[16:17]
	flat_load_dword v24, v[18:19]
	flat_load_dword v26, v[20:21]
	v_add_co_u32_e32 v2, vcc, s44, v2
	v_ashrrev_i32_e32 v51, 7, v46
	s_nop 0
	v_addc_co_u32_e32 v3, vcc, 0, v3, vcc
	flat_load_dword v30, v[2:3]
	v_lshlrev_b32_e32 v2, 13, v51
	v_lshlrev_b32_e32 v3, 2, v50
	v_add3_u32 v29, 0, v2, v3
	ds_read2st64_b32 v[2:3], v29 offset1:2
	ds_read2st64_b32 v[16:17], v29 offset0:4 offset1:6
	ds_read2st64_b32 v[18:19], v29 offset0:8 offset1:10
	ds_read2st64_b32 v[20:21], v29 offset0:12 offset1:14
	ds_read2st64_b32 v[22:23], v29 offset0:16 offset1:18
	ds_read2st64_b32 v[32:33], v29 offset0:20 offset1:22
	ds_read2st64_b32 v[36:37], v29 offset0:24 offset1:26
	ds_read2st64_b32 v[34:35], v29 offset0:28 offset1:30
	s_waitcnt lgkmcnt(0)
	v_mov_b32_e32 v38, v3
	v_mov_b32_e32 v39, v16
	v_mov_b32_e32 v40, v17
	v_mov_b32_e32 v41, v18
	v_mov_b32_e32 v42, v19
	v_mov_b32_e32 v43, v20
	s_waitcnt vmcnt(0)
	s_cmpk_eq_i32 s40, 0x1000
	s_cbranch_scc1 .Lmy_dn_norp
	v_ashrrev_i32_e32 v220, 4, v46
	v_add_u32_e32 v222, v220, v47
	v_mov_b32_e32 v8, 0
	v_mov_b32_e32 v9, 0
	v_cmp_le_i32_e32 vcc, s33, v222
	v_cmp_gt_i32_e64 s[12:13], s72, v222
	v_mov_b32_e32 v10, 0
	v_mov_b32_e32 v11, 0
	v_mov_b64_e32 v[4:5], v[8:9]
	s_and_b64 s[14:15], vcc, s[12:13]
	v_and_b32_e32 v220, 15, v46
	v_mov_b64_e32 v[6:7], v[10:11]
	s_and_saveexec_b64 s[12:13], s[14:15]
	s_cbranch_execz .LBB0_675
	v_mad_i64_i32 v[222:223], s[14:15], v222, s51, 0
	s_add_u32 s14, s39, s40
	v_lshl_or_b32 v222, v220, 4, v222
	s_addc_u32 s15, s73, s41
	v_lshl_add_u64 v[222:223], s[14:15], 0, v[222:223]
	flat_load_dwordx4 v[4:7], v[222:223]
.LBB0_675:
	s_or_b64 exec, exec, s[12:13]
	v_ashrrev_i32_e32 v222, 4, v48
	v_add_u32_e32 v222, v222, v47
	v_cmp_le_i32_e32 vcc, s33, v222
	v_cmp_gt_i32_e64 s[12:13], s72, v222
	s_and_b64 s[14:15], vcc, s[12:13]
	s_and_saveexec_b64 s[12:13], s[14:15]
	s_cbranch_execz .LBB0_677
	v_mad_i64_i32 v[222:223], s[14:15], v222, s51, 0
	s_add_u32 s14, s39, s40
	v_lshl_or_b32 v222, v220, 4, v222
	s_addc_u32 s15, s73, s41
	v_lshl_add_u64 v[222:223], s[14:15], 0, v[222:223]
	flat_load_dwordx4 v[8:11], v[222:223]
.LBB0_677:
	s_or_b64 exec, exec, s[12:13]
	v_ashrrev_i32_e32 v222, 4, v49
	v_add_u32_e32 v222, v222, v47
	v_cmp_le_i32_e32 vcc, s33, v222
	s_and_b64 s[12:13], s[10:11], vcc
	v_cmp_gt_i32_e32 vcc, s72, v222
	s_and_b64 s[14:15], s[12:13], vcc
	v_mov_b32_e32 v15, 0
	v_mov_b32_e32 v14, 0
	v_mov_b32_e32 v13, 0
	v_mov_b32_e32 v12, 0
	s_and_saveexec_b64 s[12:13], s[14:15]
	s_cbranch_execz .LBB0_679
	v_mad_i64_i32 v[222:223], s[14:15], v222, s51, 0
	s_add_u32 s14, s39, s40
	v_lshl_or_b32 v222, v220, 4, v222
	s_addc_u32 s15, s73, s41
	v_lshl_add_u64 v[222:223], s[14:15], 0, v[222:223]
	flat_load_dwordx4 v[12:15], v[222:223]

; __device__ __forceinline__ void phase_dnprep(KP kp_){ asm volatile("" : "+s"(kp_)); const Params p=load_params(kp_);
;     ...
;       { float rw[20];
;         _Pragma("unroll") for (int i=0;i<20;++i) rw[i]=raw[(tg*16+i)*128+c];
;         _Pragma("unroll") for (int i=0;i<16;++i){
;           float a=w0*rw[i]+w1*rw[i+1]+w2*rw[i+2]+w3*rw[i+3]+w4*rw[i+4];
;           o16[i]=a/(1.f+__expf(-a)); } }
.Lmy_dn_norp:
	v_pk_mul_f32 v[38:39], v[28:29], v[38:39] op_sel_hi:[0,1]
	v_pk_fma_f32 v[2:3], v[0:1], v[2:3], v[38:39] op_sel_hi:[0,1,1]
	v_pk_mul_f32 v[44:45], v[28:29], v[40:41] op_sel_hi:[0,1]
	v_pk_fma_f32 v[2:3], v[24:25], v[16:17], v[2:3] op_sel_hi:[0,1,1]
	v_pk_fma_f32 v[38:39], v[0:1], v[16:17], v[44:45] op_sel_hi:[0,1,1]
	v_pk_fma_f32 v[2:3], v[26:27], v[40:41], v[2:3] op_sel_hi:[0,1,1]
	v_pk_fma_f32 v[16:17], v[24:25], v[18:19], v[38:39] op_sel_hi:[0,1,1]
	v_pk_fma_f32 v[16:17], v[26:27], v[42:43], v[16:17] op_sel_hi:[0,1,1]
	v_pk_fma_f32 v[2:3], v[30:31], v[18:19], v[2:3] op_sel_hi:[0,1,1]
	v_mul_f32_e32 v25, 0xbfb8aa3b, v2
	v_mul_f32_e32 v27, 0xbfb8aa3b, v3
	v_exp_f32_e32 v44, v25
	v_exp_f32_e32 v45, v27
	v_pk_fma_f32 v[16:17], v[30:31], v[20:21], v[16:17] op_sel_hi:[0,1,1]
	v_mul_f32_e32 v31, 0xbfb8aa3b, v16
	v_mul_f32_e32 v38, 0xbfb8aa3b, v17
	v_pk_add_f32 v[44:45], v[44:45], 1.0 op_sel_hi:[1,0]
	v_exp_f32_e32 v52, v31
	v_exp_f32_e32 v53, v38
	v_div_scale_f32 v25, s[12:13], v45, v45, v3
	v_div_scale_f32 v31, s[12:13], v44, v44, v2
	v_rcp_f32_e32 v56, v25
	v_rcp_f32_e32 v57, v31
	v_pk_add_f32 v[52:53], v[52:53], 1.0 op_sel_hi:[1,0]
	v_div_scale_f32 v27, vcc, v3, v45, v3
	v_div_scale_f32 v55, s[14:15], v53, v53, v17
	v_fma_f32 v60, -v25, v56, 1.0
	v_rcp_f32_e32 v58, v55
	v_fma_f32 v61, -v31, v57, 1.0
	v_fmac_f32_e32 v56, v60, v56
	v_div_scale_f32 v54, s[12:13], v2, v44, v2
	v_fmac_f32_e32 v57, v61, v57
	v_mul_f32_e32 v60, v27, v56
	v_mul_f32_e32 v61, v54, v57
	v_fma_f32 v63, -v25, v60, v27
	v_fma_f32 v64, -v31, v61, v54
	v_fmac_f32_e32 v60, v63, v56
	v_fma_f32 v62, -v55, v58, 1.0
	v_fmac_f32_e32 v61, v64, v57
	v_fma_f32 v25, -v25, v60, v27
	v_div_scale_f32 v59, s[14:15], v17, v53, v17
	v_fmac_f32_e32 v58, v62, v58
	v_fma_f32 v27, -v31, v61, v54
	v_div_fmas_f32 v25, v25, v56, v60
	s_mov_b64 vcc, s[12:13]
	v_mul_f32_e32 v62, v59, v58
	v_div_fixup_f32 v3, v25, v45, v3
	v_div_fmas_f32 v25, v27, v57, v61
	v_div_scale_f32 v27, s[12:13], v52, v52, v16
	v_fma_f32 v65, -v55, v62, v59
	v_rcp_f32_e32 v31, v27
	v_fmac_f32_e32 v62, v65, v58
	v_div_fixup_f32 v2, v25, v44, v2
	v_fma_f32 v25, -v55, v62, v59
	s_mov_b64 vcc, s[14:15]
	v_div_fmas_f32 v25, v25, v58, v62
	v_div_fixup_f32 v17, v25, v53, v17
	v_fma_f32 v25, -v27, v31, 1.0
	v_pk_mul_f32 v[42:43], v[28:29], v[42:43] op_sel_hi:[0,1]
	v_fmac_f32_e32 v31, v25, v31
	v_div_scale_f32 v25, vcc, v16, v52, v16
	v_pk_fma_f32 v[18:19], v[0:1], v[18:19], v[42:43] op_sel_hi:[0,1,1]
	v_pk_fma_f32 v[18:19], v[24:25], v[20:21], v[18:19] op_sel_hi:[0,1,1]
	v_mov_b32_e32 v42, v21
	v_mov_b32_e32 v43, v22
	v_pk_fma_f32 v[18:19], v[26:27], v[42:43], v[18:19] op_sel_hi:[0,1,1]
	v_pk_fma_f32 v[18:19], v[30:31], v[22:23], v[18:19] op_sel_hi:[0,1,1]
	v_mul_f32_e32 v44, 0xbfb8aa3b, v18
	v_mul_f32_e32 v45, 0xbfb8aa3b, v19
	v_exp_f32_e32 v44, v44
	v_exp_f32_e32 v45, v45
	v_mul_f32_e32 v53, v25, v31
	v_fma_f32 v54, -v27, v53, v25
	v_fmac_f32_e32 v53, v54, v31
	v_pk_add_f32 v[44:45], v[44:45], 1.0 op_sel_hi:[1,0]
	v_fma_f32 v25, -v27, v53, v25
	v_div_scale_f32 v27, s[12:13], v45, v45, v19
	v_rcp_f32_e32 v54, v27
	v_div_fmas_f32 v25, v25, v31, v53
	v_div_fixup_f32 v16, v25, v52, v16
	v_pk_mul_f32 v[42:43], v[28:29], v[42:43] op_sel_hi:[0,1]
	v_fma_f32 v25, -v27, v54, 1.0
	v_fmac_f32_e32 v54, v25, v54
	v_div_scale_f32 v25, vcc, v19, v45, v19
	v_mul_f32_e32 v31, v25, v54
	v_fma_f32 v52, -v27, v31, v25
	v_fmac_f32_e32 v31, v52, v54
	v_fma_f32 v25, -v27, v31, v25
	v_div_scale_f32 v27, s[12:13], v44, v44, v18
	v_rcp_f32_e32 v55, v27
	v_div_fmas_f32 v25, v25, v54, v31
	v_div_fixup_f32 v19, v25, v45, v19
	v_pk_fma_f32 v[20:21], v[0:1], v[20:21], v[42:43] op_sel_hi:[0,1,1]
	v_fma_f32 v25, -v27, v55, 1.0
	v_fmac_f32_e32 v55, v25, v55
	v_div_scale_f32 v25, vcc, v18, v44, v18
	v_pk_fma_f32 v[20:21], v[24:25], v[22:23], v[20:21] op_sel_hi:[0,1,1]
	v_mov_b32_e32 v42, v23
	v_mov_b32_e32 v43, v32
	v_mul_f32_e32 v31, v25, v55
	v_pk_fma_f32 v[20:21], v[26:27], v[42:43], v[20:21] op_sel_hi:[0,1,1]
	v_pk_fma_f32 v[20:21], v[30:31], v[32:33], v[20:21] op_sel_hi:[0,1,1]
	v_mul_f32_e32 v45, 0xbfb8aa3b, v20
	v_exp_f32_e32 v52, v45
	v_mul_f32_e32 v45, 0xbfb8aa3b, v21
	v_exp_f32_e32 v53, v45
	v_fma_f32 v45, -v27, v31, v25
	v_fmac_f32_e32 v31, v45, v55
	v_fma_f32 v25, -v27, v31, v25
	v_pk_add_f32 v[52:53], v[52:53], 1.0 op_sel_hi:[1,0]
	v_div_fmas_f32 v25, v25, v55, v31
	v_div_scale_f32 v27, s[12:13], v53, v53, v21
	v_rcp_f32_e32 v45, v27
	v_div_fixup_f32 v18, v25, v44, v18
	v_pk_mul_f32 v[42:43], v[28:29], v[42:43] op_sel_hi:[0,1]
	v_pk_fma_f32 v[22:23], v[0:1], v[22:23], v[42:43] op_sel_hi:[0,1,1]
	v_fma_f32 v25, -v27, v45, 1.0
	v_fmac_f32_e32 v45, v25, v45
	v_div_scale_f32 v25, vcc, v21, v53, v21
	v_mul_f32_e32 v31, v25, v45
	v_fma_f32 v44, -v27, v31, v25
	v_fmac_f32_e32 v31, v44, v45
	v_fma_f32 v25, -v27, v31, v25
	v_div_scale_f32 v27, s[12:13], v52, v52, v20
	v_rcp_f32_e32 v54, v27
	v_div_fmas_f32 v25, v25, v45, v31
	v_div_fixup_f32 v21, v25, v53, v21
	v_mov_b32_e32 v42, v33
	v_fma_f32 v25, -v27, v54, 1.0
	v_fmac_f32_e32 v54, v25, v54
	v_div_scale_f32 v25, vcc, v20, v52, v20
	v_pk_fma_f32 v[22:23], v[24:25], v[32:33], v[22:23] op_sel_hi:[0,1,1]
	v_mov_b32_e32 v43, v36
	v_mul_f32_e32 v31, v25, v54
	v_pk_fma_f32 v[22:23], v[26:27], v[42:43], v[22:23] op_sel_hi:[0,1,1]
	v_pk_fma_f32 v[22:23], v[30:31], v[36:37], v[22:23] op_sel_hi:[0,1,1]
	v_mul_f32_e32 v44, 0xbfb8aa3b, v22
	v_mul_f32_e32 v45, 0xbfb8aa3b, v23
	v_exp_f32_e32 v44, v44
	v_exp_f32_e32 v45, v45
	v_fma_f32 v53, -v27, v31, v25
	v_fmac_f32_e32 v31, v53, v54
	v_fma_f32 v25, -v27, v31, v25
	v_pk_add_f32 v[44:45], v[44:45], 1.0 op_sel_hi:[1,0]
	v_div_fmas_f32 v25, v25, v54, v31
; __device__ __forceinline__ void phase_dnprep(KP kp_){ asm volatile("" : "+s"(kp_)); const Params p=load_params(kp_);
;     ...
;       { float rw[20];
;         _Pragma("unroll") for (int i=0;i<20;++i) rw[i]=raw[(tg*16+i)*128+c];
;         _Pragma("unroll") for (int i=0;i<16;++i){
;           float a=w0*rw[i]+w1*rw[i+1]+w2*rw[i+2]+w3*rw[i+3]+w4*rw[i+4];
;           o16[i]=a/(1.f+__expf(-a)); } }
	v_div_scale_f32 v27, s[12:13], v45, v45, v23
	v_rcp_f32_e32 v53, v27
	v_div_fixup_f32 v20, v25, v52, v20
	v_pk_mul_f32 v[42:43], v[28:29], v[42:43] op_sel_hi:[0,1]
	v_pk_fma_f32 v[32:33], v[0:1], v[32:33], v[42:43] op_sel_hi:[0,1,1]
	v_fma_f32 v25, -v27, v53, 1.0
	v_fmac_f32_e32 v53, v25, v53
	v_div_scale_f32 v25, vcc, v23, v45, v23
	v_mul_f32_e32 v31, v25, v53
	v_fma_f32 v52, -v27, v31, v25
	v_fmac_f32_e32 v31, v52, v53
	v_fma_f32 v25, -v27, v31, v25
	v_div_scale_f32 v27, s[12:13], v44, v44, v22
	v_rcp_f32_e32 v54, v27
	v_div_fmas_f32 v25, v25, v53, v31
	v_div_fixup_f32 v23, v25, v45, v23
	v_mov_b32_e32 v42, v37
	v_fma_f32 v25, -v27, v54, 1.0
	v_fmac_f32_e32 v54, v25, v54
	v_div_scale_f32 v25, vcc, v22, v44, v22
	v_pk_fma_f32 v[32:33], v[24:25], v[36:37], v[32:33] op_sel_hi:[0,1,1]
	v_mov_b32_e32 v43, v34
	v_mul_f32_e32 v31, v25, v54
	v_pk_fma_f32 v[32:33], v[26:27], v[42:43], v[32:33] op_sel_hi:[0,1,1]
	v_pk_fma_f32 v[32:33], v[30:31], v[34:35], v[32:33] op_sel_hi:[0,1,1]
	v_mul_f32_e32 v45, 0xbfb8aa3b, v32
	v_exp_f32_e32 v52, v45
	v_mul_f32_e32 v45, 0xbfb8aa3b, v33
	v_exp_f32_e32 v53, v45
	v_fma_f32 v45, -v27, v31, v25
	v_fmac_f32_e32 v31, v45, v54
	v_fma_f32 v25, -v27, v31, v25
	v_pk_add_f32 v[52:53], v[52:53], 1.0 op_sel_hi:[1,0]
	v_div_fmas_f32 v25, v25, v54, v31
	v_div_scale_f32 v27, s[12:13], v53, v53, v33
	v_rcp_f32_e32 v45, v27
	v_div_fixup_f32 v22, v25, v44, v22
	ds_read2st64_b32 v[40:41], v29 offset0:32 offset1:34
	ds_read2st64_b32 v[38:39], v29 offset0:36 offset1:38
	v_pk_mul_f32 v[42:43], v[28:29], v[42:43] op_sel_hi:[0,1]
	v_fma_f32 v25, -v27, v45, 1.0
	v_fmac_f32_e32 v45, v25, v45
	v_div_scale_f32 v25, vcc, v33, v53, v33
	v_mul_f32_e32 v31, v25, v45
	v_fma_f32 v44, -v27, v31, v25
	v_fmac_f32_e32 v31, v44, v45
	v_fma_f32 v25, -v27, v31, v25
	v_div_scale_f32 v27, s[12:13], v52, v52, v32
	v_rcp_f32_e32 v54, v27
	v_div_fmas_f32 v25, v25, v45, v31
	v_div_fixup_f32 v33, v25, v53, v33
	v_pk_fma_f32 v[36:37], v[0:1], v[36:37], v[42:43] op_sel_hi:[0,1,1]
	v_fma_f32 v25, -v27, v54, 1.0
	v_fmac_f32_e32 v54, v25, v54
	v_div_scale_f32 v25, vcc, v32, v52, v32
	v_pk_fma_f32 v[36:37], v[24:25], v[34:35], v[36:37] op_sel_hi:[0,1,1]
	v_mov_b32_e32 v42, v35
	s_waitcnt lgkmcnt(1)
	v_mov_b32_e32 v43, v40
	v_mul_f32_e32 v31, v25, v54
	v_pk_fma_f32 v[36:37], v[26:27], v[42:43], v[36:37] op_sel_hi:[0,1,1]
	v_pk_fma_f32 v[36:37], v[30:31], v[40:41], v[36:37] op_sel_hi:[0,1,1]
	v_mul_f32_e32 v44, 0xbfb8aa3b, v36
	v_mul_f32_e32 v45, 0xbfb8aa3b, v37
	v_exp_f32_e32 v44, v44
	v_exp_f32_e32 v45, v45
	v_fma_f32 v53, -v27, v31, v25
	v_fmac_f32_e32 v31, v53, v54
	v_fma_f32 v25, -v27, v31, v25
	v_pk_add_f32 v[44:45], v[44:45], 1.0 op_sel_hi:[1,0]
	v_div_fmas_f32 v25, v25, v54, v31
	v_div_scale_f32 v27, s[12:13], v45, v45, v37
	v_rcp_f32_e32 v53, v27
	v_div_fixup_f32 v32, v25, v52, v32
	v_pk_mul_f32 v[42:43], v[28:29], v[42:43] op_sel_hi:[0,1]
	v_pk_fma_f32 v[34:35], v[0:1], v[34:35], v[42:43] op_sel_hi:[0,1,1]
	v_fma_f32 v25, -v27, v53, 1.0
	v_fmac_f32_e32 v53, v25, v53
	v_div_scale_f32 v25, vcc, v37, v45, v37
	v_mul_f32_e32 v31, v25, v53
	v_fma_f32 v52, -v27, v31, v25
	v_fmac_f32_e32 v31, v52, v53
	v_div_scale_f32 v52, s[12:13], v44, v44, v36
	v_rcp_f32_e32 v54, v52
	v_fma_f32 v25, -v27, v31, v25
	v_div_fmas_f32 v25, v25, v53, v31
	v_div_fixup_f32 v25, v25, v45, v37
	v_fma_f32 v27, -v52, v54, 1.0
	v_pk_fma_f32 v[34:35], v[24:25], v[40:41], v[34:35] op_sel_hi:[0,1,1]
	v_mov_b32_e32 v40, v41
	s_waitcnt lgkmcnt(0)
	v_mov_b32_e32 v41, v38
	v_fmac_f32_e32 v54, v27, v54
	v_pk_fma_f32 v[26:27], v[26:27], v[40:41], v[34:35] op_sel_hi:[0,1,1]
	v_pk_fma_f32 v[26:27], v[30:31], v[38:39], v[26:27] op_sel_hi:[0,1,1]
	v_mul_f32_e32 v0, 0xbfb8aa3b, v26
	v_exp_f32_e32 v30, v0
	v_mul_f32_e32 v0, 0xbfb8aa3b, v27
	v_exp_f32_e32 v31, v0
	v_div_scale_f32 v37, vcc, v36, v44, v36
	v_mul_f32_e32 v45, v37, v54
	v_pk_add_f32 v[30:31], v[30:31], 1.0 op_sel_hi:[1,0]
	v_fma_f32 v0, -v52, v45, v37
	v_div_scale_f32 v28, s[12:13], v31, v31, v27
	v_rcp_f32_e32 v34, v28
	v_fmac_f32_e32 v45, v0, v54
	v_fma_f32 v0, -v52, v45, v37
	v_div_fmas_f32 v0, v0, v54, v45
	v_div_fixup_f32 v24, v0, v44, v36
	v_fma_f32 v0, -v28, v34, 1.0
	v_fmac_f32_e32 v34, v0, v34
	v_div_scale_f32 v0, vcc, v27, v31, v27
	v_mul_f32_e32 v35, v0, v34
	v_fma_f32 v36, -v28, v35, v0
	v_fmac_f32_e32 v35, v36, v34
	v_fma_f32 v0, -v28, v35, v0
	v_div_scale_f32 v28, s[12:13], v30, v30, v26
	v_rcp_f32_e32 v36, v28
	v_div_fmas_f32 v0, v0, v34, v35
	v_div_fixup_f32 v27, v0, v31, v27
	s_mov_b64 s[12:13], -1
	v_fma_f32 v0, -v28, v36, 1.0
	v_fmac_f32_e32 v36, v0, v36
	v_div_scale_f32 v0, vcc, v26, v30, v26
	v_mul_f32_e32 v31, v0, v36
	v_fma_f32 v34, -v28, v31, v0
	v_fmac_f32_e32 v31, v34, v36
	v_fma_f32 v0, -v28, v31, v0
	v_div_fmas_f32 v0, v0, v36, v31
	v_div_fixup_f32 v26, v0, v30, v26
	s_andn2_b64 vcc, exec, s[42:43]
	s_cbranch_vccnz .LBB0_688
; __device__ __forceinline__ void phase_dnprep(KP kp_){ asm volatile("" : "+s"(kp_)); const Params p=load_params(kp_);
;     ...
;         _Pragma("unroll") for (int i=0;i<16;++i) tmp[(tg*16+i)*128+c]=o16[i];
;         __syncthreads();
;         { int t=tid>>3, c0=(tid&7)*16; float ss=0.f;
;           _Pragma("unroll") for(int cc=0;cc<16;++cc){ float s_=tmp[t*128+c0+cc]; ss+=s_*s_; }
;           ss+=__shfl_xor(ss,1); ss+=__shfl_xor(ss,2); ss+=__shfl_xor(ss,4);
;           if ((tid&7)==0) scl[t]=rsqrtf(ss+EPSV)*(which==0?0.08838834764831845f:1.f); }
	v_ashrrev_i32_e32 v0, 3, v46
	v_and_b32_e32 v52, 7, v46
	ds_write2st64_b32 v29, v2, v3 offset0:136 offset1:138
	ds_write2st64_b32 v29, v16, v17 offset0:140 offset1:142
	ds_write2st64_b32 v29, v18, v19 offset0:144 offset1:146
	ds_write2st64_b32 v29, v20, v21 offset0:148 offset1:150
	ds_write2st64_b32 v29, v22, v23 offset0:152 offset1:154
	ds_write2st64_b32 v29, v32, v33 offset0:156 offset1:158
	ds_write2st64_b32 v29, v24, v25 offset0:160 offset1:162
	ds_write2st64_b32 v29, v26, v27 offset0:164 offset1:166
	v_lshlrev_b32_e32 v28, 9, v0
	v_lshlrev_b32_e32 v29, 6, v52
	v_add3_u32 v42, 0, v28, v29
	s_waitcnt lgkmcnt(0)
	s_barrier
	ds_read_b128 v[28:31], v42 offset:34816
	ds_read_b128 v[34:37], v42 offset:34832
	ds_read_b128 v[38:41], v42 offset:34848
	ds_read_b128 v[42:45], v42 offset:34864
	s_waitcnt lgkmcnt(3)
	v_mul_f32_e32 v29, v29, v29
	v_fmac_f32_e32 v29, v28, v28
	v_fmac_f32_e32 v29, v30, v30
	v_fmac_f32_e32 v29, v31, v31
	s_waitcnt lgkmcnt(2)
	v_fmac_f32_e32 v29, v34, v34
	v_fmac_f32_e32 v29, v35, v35
	v_fmac_f32_e32 v29, v36, v36
	v_fmac_f32_e32 v29, v37, v37
	s_waitcnt lgkmcnt(1)
	v_fmac_f32_e32 v29, v38, v38
	v_fmac_f32_e32 v29, v39, v39
	v_fmac_f32_e32 v29, v40, v40
	v_fmac_f32_e32 v29, v41, v41
	v_and_b32_e32 v30, 64, v85
	s_waitcnt lgkmcnt(0)
	v_fmac_f32_e32 v29, v42, v42
	v_xor_b32_e32 v28, 1, v85
	v_add_u32_e32 v30, 64, v30
	v_fmac_f32_e32 v29, v43, v43
	v_cmp_lt_i32_e32 vcc, v28, v30
	v_fmac_f32_e32 v29, v44, v44
	v_fmac_f32_e32 v29, v45, v45
	v_cndmask_b32_e32 v28, v85, v28, vcc
	v_lshlrev_b32_e32 v28, 2, v28
	ds_bpermute_b32 v28, v28, v29
	s_waitcnt lgkmcnt(0)
	v_add_f32_e32 v28, v29, v28
	v_xor_b32_e32 v29, 2, v85
	v_cmp_lt_i32_e32 vcc, v29, v30
	s_nop 1
	v_cndmask_b32_e32 v29, v85, v29, vcc
	v_lshlrev_b32_e32 v29, 2, v29
	ds_bpermute_b32 v29, v29, v28
	s_waitcnt lgkmcnt(0)
	v_add_f32_e32 v28, v28, v29
	v_xor_b32_e32 v29, 4, v85
	v_cmp_lt_i32_e32 vcc, v29, v30
	s_nop 1
	v_cndmask_b32_e32 v29, v85, v29, vcc
	v_lshlrev_b32_e32 v29, 2, v29
	ds_bpermute_b32 v29, v29, v28
	v_cmp_eq_u32_e32 vcc, 0, v52
	s_and_saveexec_b64 s[12:13], vcc
	s_cbranch_execz .LBB0_683
	s_waitcnt lgkmcnt(0)
	v_add_f32_e32 v28, v28, v29
	v_add_f32_e32 v28, 0x358637bd, v28
	v_mul_f32_e32 v29, 0x4b800000, v28
	v_cmp_gt_f32_e32 vcc, s66, v28
	s_cmp_eq_u32 s40, 0
	v_lshl_add_u32 v0, v0, 2, 0
	v_cndmask_b32_e32 v28, v28, v29, vcc
	v_rsq_f32_e32 v28, v28
	v_add_u32_e32 v0, 0x21400, v0
	v_mul_f32_e32 v29, 0x45800000, v28
	v_cndmask_b32_e32 v28, v28, v29, vcc
	s_cselect_b64 vcc, -1, 0
	v_cndmask_b32_e32 v29, 1.0, v87, vcc
	v_mul_f32_e32 v28, v29, v28
	ds_write_b32 v0, v28
